# hand-written FFN weight transposer (DPP exchange, double-buffered loads); Fourier GEMM moved to WGs 64-255 and D->E grid barrier removed (independent phases)
# speedup vs baseline: 1.0110x; 1.0110x over previous
; #define PG8_STAGE(bufoff, gbase, voff) do { _Pragma("unroll") for (int _i = 0; _i < 2; ++_i) \
;         __builtin_amdgcn_global_load_lds((const unsigned*)((const char*)(gbase) + (voff)[_i]), (LAS unsigned*)(lds + (bufoff) + ldsw + _i * 8192), 16, 0, 0); } while (0)
; #define PG8_WAIT_V(n) asm volatile("s_waitcnt vmcnt(" #n ")" ::: "memory")
; template <class Epi>
; __device__ __forceinline__ void gemm_phase(LAS unsigned char* lds, const Sched& S, const int K, const Epi& E) {
;     ...
;     const int wid = __builtin_amdgcn_readfirstlane(tid >> 6), lane = tid & 63, wr = wid >> 2, wc = wid & 3, fr = lane & 15, fq = lane >> 4;
;     const int nt = K / BK;
;     unsigned voffA[2], voffB[2];
; #pragma unroll
;     for (int i = 0; i < 2; ++i) { int R, C; stage_rc(tid * 16 + i * 8192, R, C); const int Rb = Epi::PERM ? ((R & ~31) + perm32(R & 31)) : R;
;         const int RbT = Epi::BMAP ? ((Rb >> 4) + 256 * (Rb & 15)) : Rb;
;         voffA[i] = (unsigned)(R * S.lda + C) * 2u; voffB[i] = (unsigned)(RbT * S.ldb + C) * 2u; }
;     const size_t kstep = (size_t)(BK * 2);
;     const size_t hstepA = (size_t)HALF * S.lda * 2, hstepB = (size_t)(Epi::BMAP ? 8 : HALF) * S.ldb * 2;
;     const unsigned ldsw = (unsigned)wid * 1024u;
;     const int aoff = lds_byte(wr * 64 + fr, fq * 8), boff = lds_byte(wc * 32 + fr, fq * 8);
;     ...
;     Unit cur, nxt; int ui = 0;
;     if (!S.next(0, cur)) return;
;     f32x4 acc[2][2][4][2];
; #pragma unroll
;     for (int a = 0; a < 2; ++a)
; #pragma unroll
;         for (int b = 0; b < 2; ++b)
; #pragma unroll
;             for (int m = 0; m < 4; ++m)
; #pragma unroll
;                 for (int n = 0; n < 2; ++n) acc[a][b][m][n] = (f32x4){0.f, 0.f, 0.f, 0.f};
;     bf16x8 At[4][2], B0[2][2], B1[2][2];
;     const char* cA = cur.A; const char* cB = cur.B;
;     PG8_STAGE(PG8_SB(0, 0), cB, voffB); PG8_STAGE(PG8_SB(0, 1), cB + hstepB, voffB); PG8_STAGE(PG8_SA(0, 0), cA, voffA); PG8_STAGE(PG8_SA(0, 1), cA + hstepA, voffA);
;     if (wr == 1) PG8_BAR;
;     PG8_WAIT_V(2); PG8_BAR;
;     PG8_STAGE(PG8_SB(1, 0), cB + kstep, voffB); PG8_STAGE(PG8_SA(1, 0), cA + kstep, voffA); PG8_STAGE(PG8_SB(1, 1), cB + hstepB + kstep, voffB);
; __global__ void __launch_bounds__(NTHREADS, 2) mega_fwd(Args a) {
;     ...
;             { pg8::Sched S{(const char*)D256, (const char*)VT, 0, 0, 512, 512, 1, 192, 1, G, bx, 0, 8}; EpiFour2 E{SLOT1}; pg8::gemm_phase(lds, S, 512, E); }
.LBB0_737:
	s_andn2_b64 vcc, exec, s[28:29]
	s_cbranch_vccnz .LBB0_822
	v_readlane_b32 s34, v253, 36
	s_mov_b64 s[38:39], s[22:23]
	s_sub_i32 s0, s68, 64
	s_mov_b64 s[28:29], s[20:21]
	s_mov_b32 s2, s34
	s_waitcnt vmcnt(0)
	v_mov_b32_e32 v4, v175
	s_cmpk_gt_u32 s0, 0xbf
	v_readfirstlane_b32 s40, v4
	v_readlane_b32 s35, v253, 37
	s_cbranch_scc1 .LBB0_754
	v_lshlrev_b32_e32 v0, 4, v4
	v_add_u32_e32 v1, 0x2000, v0
	v_ashrrev_i32_e32 v2, 31, v1
	v_lshrrev_b32_e32 v2, 22, v2
	v_add_u32_e32 v2, v1, v2
	v_ashrrev_i32_e32 v5, 10, v2
	v_mul_i32_i24_e32 v2, 0x400, v5
	v_sub_u32_e32 v1, v1, v2
	v_lshrrev_b32_e32 v2, 4, v1
	v_bitop3_b32 v1, v2, v1, 32 bitop3:0x6c
	v_ashrrev_i32_e32 v2, 31, v1
	v_lshrrev_b32_e32 v2, 26, v2
	v_add_u32_e32 v2, v1, v2
	v_lshlrev_b32_e32 v3, 3, v5
	v_ashrrev_i32_e32 v6, 6, v2
	v_and_b32_e32 v3, -16, v3
	v_add_u32_e32 v3, v6, v3
	v_and_b32_e32 v7, 3, v6
	s_mov_b32 s4, 0x3fffe0
	v_lshrrev_b32_e32 v8, 2, v3
	v_lshlrev_b32_e32 v9, 1, v3
	v_and_b32_e32 v2, 0xc0, v2
	v_and_or_b32 v7, v3, s4, v7
	v_and_b32_e32 v8, 4, v8
	v_and_b32_e32 v9, 24, v9
	v_sub_u32_e32 v1, v1, v2
	v_or3_b32 v8, v7, v8, v9
	v_lshlrev_b32_e32 v7, 5, v5
	v_ashrrev_i16_sdwa v1, v249, sext(v1) dst_sel:DWORD dst_unused:UNUSED_PAD src0_sel:DWORD src1_sel:BYTE_0
	v_and_b32_e32 v9, 32, v7
	v_bfe_i32 v7, v1, 0, 16
	v_add_lshl_u32 v1, v9, v7, 1
	v_lshl_add_u32 v128, v8, 10, v1
	v_lshl_add_u32 v130, v3, 10, v1
	v_bfe_i32 v1, v4, 27, 1
	v_lshrrev_b32_e32 v1, 22, v1
	v_add_u32_e32 v1, v0, v1
	v_and_b32_e32 v1, 0xfffffc00, v1
	v_sub_u32_e32 v0, v0, v1
	v_lshrrev_b32_e32 v1, 4, v0
	v_ashrrev_i32_e32 v2, 31, v4
	v_bitop3_b32 v0, v1, v0, 32 bitop3:0x6c
	v_lshrrev_b32_e32 v2, 26, v2
	v_ashrrev_i32_e32 v1, 31, v0
	v_add_u32_e32 v2, v4, v2
	s_add_u32 s34, s38, 0x8850000
	v_lshrrev_b32_e32 v1, 26, v1
	v_ashrrev_i32_e32 v9, 6, v2
	s_addc_u32 s35, s39, 0
	v_add_u32_e32 v1, v0, v1
	v_lshlrev_b32_e32 v2, 3, v9
	s_add_u32 s31, s38, 0x5850000
	v_ashrrev_i32_e32 v8, 6, v1
	v_and_b32_e32 v2, -16, v2
	s_addc_u32 s33, s39, 0
	v_add_u32_e32 v2, v8, v2
	s_and_b32 s29, s0, 7
	v_and_b32_e32 v3, 3, v8
	v_lshrrev_b32_e32 v10, 2, v2
	v_lshlrev_b32_e32 v11, 1, v2
	v_and_b32_e32 v1, 0xc0, v1
	s_lshr_b32 s28, s0, 3
	s_mul_i32 s29, s29, 24
	s_ashr_i32 s41, s40, 6
	v_and_or_b32 v3, v2, s4, v3
	v_and_b32_e32 v10, 4, v10
	v_and_b32_e32 v11, 24, v11
	v_sub_u32_e32 v0, v0, v1
	s_add_i32 s64, s29, s28
	s_ashr_i32 s42, s40, 8
	s_lshl_b32 s54, s41, 10
	v_or3_b32 v3, v3, v10, v11
	v_lshlrev_b32_e32 v10, 5, v9
	v_ashrrev_i16_sdwa v0, v249, sext(v0) dst_sel:DWORD dst_unused:UNUSED_PAD src0_sel:DWORD src1_sel:BYTE_0
	s_lshl_b32 s28, s64, 18
	v_and_b32_e32 v11, 32, v10
	v_bfe_i32 v10, v0, 0, 16
	s_add_u32 s48, s31, s28
	v_add_lshl_u32 v0, v11, v10, 1
	s_addc_u32 s49, s33, 0
	s_add_i32 s55, s54, 0
	v_lshl_add_u32 v132, v3, 10, v0
	s_add_i32 m0, s55, 0x10000
	v_lshl_add_u32 v134, v2, 10, v0
	global_load_lds_dwordx4 v132, s[48:49]
	s_add_i32 m0, s55, 0x12000
	s_add_u32 s28, s48, 0x20000
	global_load_lds_dwordx4 v128, s[48:49]
	s_addc_u32 s29, s49, 0
	s_add_i32 m0, s55, 0x14000
	s_add_i32 s57, s55, 0x2000
	global_load_lds_dwordx4 v132, s[28:29]
	s_add_i32 m0, s55, 0x16000
	v_mov_b32_e32 v133, v173
	global_load_lds_dwordx4 v128, s[28:29]
	s_mov_b32 m0, s55
	s_add_u32 s28, s38, 0x8870000
	global_load_lds_dwordx4 v134, s[34:35]
	s_mov_b32 m0, s57
	s_addc_u32 s29, s39, 0
	s_add_i32 s58, s55, 0x4000
	global_load_lds_dwordx4 v130, s[34:35]
	s_mov_b32 m0, s58
	s_add_i32 s59, s55, 0x6000
	global_load_lds_dwordx4 v134, s[28:29]
	s_mov_b32 m0, s59
	v_mov_b32_e32 v129, v173
	global_load_lds_dwordx4 v130, s[28:29]
	s_cmp_eq_u32 s42, 1
	v_lshl_add_u64 v[0:1], s[48:49], 0, v[132:133]
	s_cselect_b64 s[28:29], -1, 0
	s_cmp_lg_u32 s42, 1
	v_lshl_add_u64 v[2:3], s[48:49], 0, v[128:129]
	s_cbranch_scc1 .LBB0_741
	s_barrier

.LBB0_754:
	s_add_i32 s0, s58, 4
	s_cmp_ge_i32 s0, s25
	s_branch .LBB0_822
	v_readlane_b32 s34, v253, 40
	v_readlane_b32 s35, v253, 41
	s_mov_b64 s[28:29], -1
	s_and_b64 vcc, exec, s[34:35]
	s_cbranch_vccz .LBB0_809
	s_waitcnt vmcnt(0)
	s_waitcnt vmcnt(0) lgkmcnt(0)
	s_barrier
	s_mov_b64 s[28:29], exec
	v_readlane_b32 s34, v253, 2
	v_readlane_b32 s35, v253, 3
	s_and_b64 s[34:35], s[28:29], s[34:35]
	s_mov_b64 exec, s[34:35]
	s_cbranch_execz .LBB0_808
	s_add_i32 s2, 0, 0x20000
	v_mov_b32_e32 v0, s2
	s_waitcnt vmcnt(0) expcnt(0) lgkmcnt(0)
	ds_read_b32 v2, v0
	v_readlane_b32 s4, v254, 49
	s_waitcnt lgkmcnt(0)
	v_cmp_ne_u32_e32 vcc, 0, v2
	v_mov_b32_e32 v0, s4
	ds_read_b32 v0, v0
	v_readlane_b32 s4, v253, 42
	s_cbranch_vccnz .LBB0_772
	s_mov_b32 s31, 1
	s_branch .LBB0_760

; #define LAS __attribute__((address_space(3)))
; __device__ __forceinline__ int tid_l() { int t = threadIdx.x; asm volatile("" : "+v"(t)); return t; }
; __device__ __forceinline__ unsigned cvt_pk_bf16(float lo, float hi) { unsigned r; asm("v_cvt_pk_bf16_f32 %0, %1, %2" : "=v"(r) : "v"(lo), "v"(hi)); return r; }
; template <class SEL, class CTX>
; __device__ __forceinline__ void transpose_run(LAS unsigned char* lds, const CTX& ctx, int t0, int t1, int stride) {
;     const int tid = tid_l();
;     LAS unsigned* tl = (LAS unsigned*)lds;
;     const int k = tid >> 3, n8 = (tid & 7) * 8;
;     f32x4 v[4][2];
;     TrDesc d; int lt;
;     if (t0 < t1) { SEL::get(ctx, t0, d, lt); const int nkt = d.K >> 6, kt = lt % nkt, ct = lt / nkt;
;         const float* s = d.src + (size_t)(kt * 64 + k) * d.ldsrc + d.c0 + ct * 256 + n8;
; #pragma unroll
;         for (int q = 0; q < 4; ++q) { v[q][0] = *(const f32x4*)(s + q * 64); v[q][1] = *(const f32x4*)(s + q * 64 + 4); } }
;     for (int t = t0; t < t1; t += stride) {
;         SEL::get(ctx, t, d, lt);
;         const int nkt = d.K >> 6, kt = lt % nkt, ct = lt / nkt;
;         unsigned w[4][4];
; #pragma unroll
;         for (int q = 0; q < 4; ++q)
; #pragma unroll
;             for (int j = 0; j < 4; ++j) { const float lo = v[q][0][j], hi = v[q][1][j];
;                 const float recv = __shfl_xor((k & 1) ? lo : hi, 8);
;                 w[q][j] = (k & 1) ? cvt_pk_bf16(recv, hi) : cvt_pk_bf16(lo, recv); }
;         if (t + stride < t1) { TrDesc dn; int ltn; SEL::get(ctx, t + stride, dn, ltn); const int nktn = dn.K >> 6, ktn = ltn % nktn, ctn = ltn / nktn;
;             const float* s = dn.src + (size_t)(ktn * 64 + k) * dn.ldsrc + dn.c0 + ctn * 256 + n8;
; #pragma unroll
;             for (int q = 0; q < 4; ++q) { v[q][0] = *(const f32x4*)(s + q * 64); v[q][1] = *(const f32x4*)(s + q * 64 + 4); } }
.LBB0_841:
	s_cmp_lt_i32 s33, 32
	s_cbranch_scc1 .LBB0_913
	v_writelane_b32 v255, s0, 24
	v_writelane_b32 v255, s2, 25
	v_writelane_b32 v255, s28, 26
	v_writelane_b32 v255, s29, 27
	v_writelane_b32 v255, s33, 28
	v_writelane_b32 v255, s34, 29
	v_writelane_b32 v255, s35, 30
	v_writelane_b32 v255, s36, 31
	v_writelane_b32 v255, s37, 32
	v_writelane_b32 v255, s38, 33
	v_writelane_b32 v255, s39, 34
	v_writelane_b32 v255, s40, 35
	v_writelane_b32 v255, s41, 36
	v_writelane_b32 v255, s44, 37
	v_writelane_b32 v255, s45, 38
	v_writelane_b32 v255, s46, 39
	v_writelane_b32 v255, s47, 44
	v_writelane_b32 v255, s48, 45
	v_writelane_b32 v255, s49, 46
	v_writelane_b32 v255, s50, 47
	v_writelane_b32 v255, s51, 48
	v_writelane_b32 v255, s52, 49
	v_writelane_b32 v255, s53, 50
	v_writelane_b32 v255, s54, 51
	v_writelane_b32 v255, s55, 52
	v_writelane_b32 v255, s56, 53
	v_writelane_b32 v255, s57, 54
	v_writelane_b32 v255, s58, 55
	v_writelane_b32 v255, s59, 56
	v_writelane_b32 v255, s90, 57
	v_writelane_b32 v255, vcc_lo, 58
	v_writelane_b32 v255, vcc_hi, 59
	s_sub_i32 s0, s33, 32
	s_add_i32 s0, s0, 0
	s_sub_i32 s2, s31, 32
	s_mul_i32 s28, s30, 0x2c00000
	v_readlane_b32 s44, v253, 28
	v_readlane_b32 s45, v253, 29
	v_readlane_b32 s46, v253, 30
	v_readlane_b32 s47, v253, 31
	v_readlane_b32 s48, v253, 32
	v_readlane_b32 s49, v253, 33
	s_nop 3
	s_add_u32 s44, s44, s28
	s_addc_u32 s45, s45, 0
	s_add_u32 s46, s46, s28
	s_addc_u32 s47, s47, 0
	s_add_u32 s48, s48, s28
	s_addc_u32 s49, s49, 0
	s_add_u32 s50, s22, 0x1650000
	s_addc_u32 s51, s23, 0
	s_add_u32 s52, s22, 0x4250000
	s_addc_u32 s53, s23, 0
	v_lshrrev_b32_e32 v100, 3, v175
	v_and_b32_e32 v96, 7, v175
	v_lshlrev_b32_e32 v101, 5, v96
	v_and_b32_e32 v97, 1, v100
	v_cmp_ne_u32_e32 vcc, 0, v97
	v_lshlrev_b32_e32 v98, 3, v96
	v_lshl_add_u32 v98, v97, 2, v98
	v_mul_u32_u24_e32 v98, 33, v98
	v_lshrrev_b32_e32 v99, 1, v100
	v_add_u32_e32 v98, v98, v99
	v_lshlrev_b32_e32 v102, 2, v98
	v_mul_u32_u24_e32 v98, 33, v100
	v_lshl_add_u32 v98, v96, 2, v98
	v_lshlrev_b32_e32 v103, 2, v98
	v_lshlrev_b32_e32 v99, 4, v96
	v_lshl_add_u32 v104, v100, 12, v99
	v_mul_u32_u24_e32 v98, 0x2c00, v100
	v_add_u32_e32 v105, v98, v99
	s_mov_b32 s33, s0
	s_cmpk_ge_u32 s33, 0x580
	s_cselect_b32 s34, 1, 0
	s_cmpk_ge_u32 s33, 0x2c0
	s_cselect_b32 s35, 1, 0
	s_add_i32 s36, s34, s35
	s_mul_i32 s36, s36, 0x2c0
	s_sub_i32 s36, s33, s36
	s_sub_i32 s35, s35, s34
	s_mul_hi_u32 s37, s36, 0x2e8ba2f
	s_mul_i32 s38, s37, 0x58
	s_sub_i32 s38, s36, s38
	s_lshr_b32 s39, s36, 5
	s_and_b32 s40, s36, 31
	s_cmp_eq_u32 s34, 1
	s_cselect_b32 s37, s37, s39
	s_cselect_b32 s38, s38, s40
	s_mov_b32 s58, 0x5800
	s_cselect_b32 s58, 0x2000, s58
	s_cselect_b32 s54, s48, s44
	s_cselect_b32 s55, s49, s45
	s_cmp_eq_u32 s35, 1
	s_cselect_b32 s54, s46, s54
	s_cselect_b32 s55, s47, s55
	s_lshl_b32 s39, s38, 6
	s_mul_i32 s39, s39, s58
	s_lshl_b32 s40, s37, 10
	s_add_u32 s39, s39, s40
	s_add_u32 s54, s54, s39
	s_addc_u32 s55, s55, 0
	v_mad_u32_u24 v106, v100, s58, v101
	global_load_dwordx4 v[0:3], v106, s[54:55]
	global_load_dwordx4 v[4:7], v106, s[54:55] offset:16
	global_load_dwordx4 v[8:11], v106, s[54:55] offset:256
	global_load_dwordx4 v[12:15], v106, s[54:55] offset:272
	global_load_dwordx4 v[16:19], v106, s[54:55] offset:512
	global_load_dwordx4 v[20:23], v106, s[54:55] offset:528
	global_load_dwordx4 v[24:27], v106, s[54:55] offset:768
	global_load_dwordx4 v[28:31], v106, s[54:55] offset:784
.Lfce_loop:
	s_add_i32 s33, s0, s2
	s_cmp_lt_u32 s33, 1056
	s_cselect_b32 s33, s33, s0
	s_cmpk_ge_u32 s33, 0x580
	s_cselect_b32 s34, 1, 0
	s_cmpk_ge_u32 s33, 0x2c0
	s_cselect_b32 s35, 1, 0
	s_add_i32 s36, s34, s35
	s_mul_i32 s36, s36, 0x2c0
	s_sub_i32 s36, s33, s36
	s_sub_i32 s35, s35, s34
	s_mul_hi_u32 s37, s36, 0x2e8ba2f
	s_mul_i32 s38, s37, 0x58
	s_sub_i32 s38, s36, s38
	s_lshr_b32 s39, s36, 5
	s_and_b32 s40, s36, 31
	s_cmp_eq_u32 s34, 1
	s_cselect_b32 s37, s37, s39
	s_cselect_b32 s38, s38, s40
	s_mov_b32 s58, 0x5800
	s_cselect_b32 s58, 0x2000, s58
	s_cselect_b32 s54, s48, s44
	s_cselect_b32 s55, s49, s45
	s_cmp_eq_u32 s35, 1
	s_cselect_b32 s54, s46, s54
	s_cselect_b32 s55, s47, s55
	s_lshl_b32 s39, s38, 6
	s_mul_i32 s39, s39, s58
	s_lshl_b32 s40, s37, 10
	s_add_u32 s39, s39, s40
	s_add_u32 s54, s54, s39
	s_addc_u32 s55, s55, 0
	v_mad_u32_u24 v106, v100, s58, v101
	global_load_dwordx4 v[32:35], v106, s[54:55]
	global_load_dwordx4 v[36:39], v106, s[54:55] offset:16
	global_load_dwordx4 v[40:43], v106, s[54:55] offset:256
	global_load_dwordx4 v[44:47], v106, s[54:55] offset:272
	global_load_dwordx4 v[48:51], v106, s[54:55] offset:512
	global_load_dwordx4 v[52:55], v106, s[54:55] offset:528
	global_load_dwordx4 v[56:59], v106, s[54:55] offset:768
	global_load_dwordx4 v[60:63], v106, s[54:55] offset:784
	s_waitcnt vmcnt(8)
; #define LAS __attribute__((address_space(3)))
; __device__ __forceinline__ unsigned cvt_pk_bf16(float lo, float hi) { unsigned r; asm("v_cvt_pk_bf16_f32 %0, %1, %2" : "=v"(r) : "v"(lo), "v"(hi)); return r; }
; template <class SEL, class CTX>
; __device__ __forceinline__ void transpose_run(LAS unsigned char* lds, const CTX& ctx, int t0, int t1, int stride) {
;     ...
;         for (int q = 0; q < 4; ++q)
; #pragma unroll
;             for (int j = 0; j < 4; ++j) { const float lo = v[q][0][j], hi = v[q][1][j];
;                 const float recv = __shfl_xor((k & 1) ? lo : hi, 8);
;                 w[q][j] = (k & 1) ? cvt_pk_bf16(recv, hi) : cvt_pk_bf16(lo, recv); }
;         if (t + stride < t1) { TrDesc dn; int ltn; SEL::get(ctx, t + stride, dn, ltn); const int nktn = dn.K >> 6, ktn = ltn % nktn, ctn = ltn / nktn;
;             const float* s = dn.src + (size_t)(ktn * 64 + k) * dn.ldsrc + dn.c0 + ctn * 256 + n8;
; #pragma unroll
;             for (int q = 0; q < 4; ++q) { v[q][0] = *(const f32x4*)(s + q * 64); v[q][1] = *(const f32x4*)(s + q * 64 + 4); } }
; #pragma unroll
;         for (int q = 0; q < 4; ++q)
; #pragma unroll
;             for (int j = 0; j < 4; ++j) tl[(q * 64 + n8 + j + ((k & 1) ? 4 : 0)) * 33 + (k >> 1)] = w[q][j];
;         __syncthreads();
;         { const int n = tid >> 3, k8 = (tid & 7) * 8;
; #pragma unroll
;           for (int q = 0; q < 4; ++q) {
;               const LAS unsigned* p = tl + (q * 64 + n) * 33 + (k8 >> 1);
;               u32x4 ww; ww.x = p[0]; ww.y = p[1]; ww.z = p[2]; ww.w = p[3];
;               const int cc = ct * 256 + q * 64 + n;
;               const int drow = d.mode == 0 ? d.doff + cc : ((cc >> 7) * 256 + (cc & 127) + (d.mode == 2 ? 128 : 0));
;               *(u32x4*)(d.dst + (size_t)drow * d.K + kt * 64 + k8) = ww; } }
	v_mov_b32_dpp v64, v0 row_ror:8 row_mask:0xf bank_mask:0xf
	v_mov_b32_dpp v65, v4 row_ror:8 row_mask:0xf bank_mask:0xf
	v_cvt_pk_bf16_f32 v66, v0, v64
	v_cvt_pk_bf16_f32 v67, v65, v4
	v_cndmask_b32_e32 v66, v66, v67, vcc
	ds_write_b32 v102, v66 offset:0
	v_mov_b32_dpp v68, v1 row_ror:8 row_mask:0xf bank_mask:0xf
	v_mov_b32_dpp v69, v5 row_ror:8 row_mask:0xf bank_mask:0xf
	v_cvt_pk_bf16_f32 v70, v1, v68
	v_cvt_pk_bf16_f32 v71, v69, v5
	v_cndmask_b32_e32 v70, v70, v71, vcc
	ds_write_b32 v102, v70 offset:132
	v_mov_b32_dpp v72, v2 row_ror:8 row_mask:0xf bank_mask:0xf
	v_mov_b32_dpp v73, v6 row_ror:8 row_mask:0xf bank_mask:0xf
	v_cvt_pk_bf16_f32 v74, v2, v72
	v_cvt_pk_bf16_f32 v75, v73, v6
	v_cndmask_b32_e32 v74, v74, v75, vcc
	ds_write_b32 v102, v74 offset:264
	v_mov_b32_dpp v76, v3 row_ror:8 row_mask:0xf bank_mask:0xf
	v_mov_b32_dpp v77, v7 row_ror:8 row_mask:0xf bank_mask:0xf
	v_cvt_pk_bf16_f32 v78, v3, v76
	v_cvt_pk_bf16_f32 v79, v77, v7
	v_cndmask_b32_e32 v78, v78, v79, vcc
	ds_write_b32 v102, v78 offset:396
	v_mov_b32_dpp v64, v8 row_ror:8 row_mask:0xf bank_mask:0xf
	v_mov_b32_dpp v65, v12 row_ror:8 row_mask:0xf bank_mask:0xf
	v_cvt_pk_bf16_f32 v66, v8, v64
	v_cvt_pk_bf16_f32 v67, v65, v12
	v_cndmask_b32_e32 v66, v66, v67, vcc
	ds_write_b32 v102, v66 offset:8448
	v_mov_b32_dpp v68, v9 row_ror:8 row_mask:0xf bank_mask:0xf
	v_mov_b32_dpp v69, v13 row_ror:8 row_mask:0xf bank_mask:0xf
	v_cvt_pk_bf16_f32 v70, v9, v68
	v_cvt_pk_bf16_f32 v71, v69, v13
	v_cndmask_b32_e32 v70, v70, v71, vcc
	ds_write_b32 v102, v70 offset:8580
	v_mov_b32_dpp v72, v10 row_ror:8 row_mask:0xf bank_mask:0xf
	v_mov_b32_dpp v73, v14 row_ror:8 row_mask:0xf bank_mask:0xf
	v_cvt_pk_bf16_f32 v74, v10, v72
	v_cvt_pk_bf16_f32 v75, v73, v14
	v_cndmask_b32_e32 v74, v74, v75, vcc
	ds_write_b32 v102, v74 offset:8712
	v_mov_b32_dpp v76, v11 row_ror:8 row_mask:0xf bank_mask:0xf
	v_mov_b32_dpp v77, v15 row_ror:8 row_mask:0xf bank_mask:0xf
	v_cvt_pk_bf16_f32 v78, v11, v76
	v_cvt_pk_bf16_f32 v79, v77, v15
	v_cndmask_b32_e32 v78, v78, v79, vcc
	ds_write_b32 v102, v78 offset:8844
	v_mov_b32_dpp v64, v16 row_ror:8 row_mask:0xf bank_mask:0xf
	v_mov_b32_dpp v65, v20 row_ror:8 row_mask:0xf bank_mask:0xf
	v_cvt_pk_bf16_f32 v66, v16, v64
	v_cvt_pk_bf16_f32 v67, v65, v20
	v_cndmask_b32_e32 v66, v66, v67, vcc
	ds_write_b32 v102, v66 offset:16896
	v_mov_b32_dpp v68, v17 row_ror:8 row_mask:0xf bank_mask:0xf
	v_mov_b32_dpp v69, v21 row_ror:8 row_mask:0xf bank_mask:0xf
	v_cvt_pk_bf16_f32 v70, v17, v68
	v_cvt_pk_bf16_f32 v71, v69, v21
	v_cndmask_b32_e32 v70, v70, v71, vcc
	ds_write_b32 v102, v70 offset:17028
	v_mov_b32_dpp v72, v18 row_ror:8 row_mask:0xf bank_mask:0xf
	v_mov_b32_dpp v73, v22 row_ror:8 row_mask:0xf bank_mask:0xf
	v_cvt_pk_bf16_f32 v74, v18, v72
	v_cvt_pk_bf16_f32 v75, v73, v22
	v_cndmask_b32_e32 v74, v74, v75, vcc
	ds_write_b32 v102, v74 offset:17160
	v_mov_b32_dpp v76, v19 row_ror:8 row_mask:0xf bank_mask:0xf
	v_mov_b32_dpp v77, v23 row_ror:8 row_mask:0xf bank_mask:0xf
	v_cvt_pk_bf16_f32 v78, v19, v76
	v_cvt_pk_bf16_f32 v79, v77, v23
	v_cndmask_b32_e32 v78, v78, v79, vcc
	ds_write_b32 v102, v78 offset:17292
	v_mov_b32_dpp v64, v24 row_ror:8 row_mask:0xf bank_mask:0xf
	v_mov_b32_dpp v65, v28 row_ror:8 row_mask:0xf bank_mask:0xf
	v_cvt_pk_bf16_f32 v66, v24, v64
	v_cvt_pk_bf16_f32 v67, v65, v28
	v_cndmask_b32_e32 v66, v66, v67, vcc
	ds_write_b32 v102, v66 offset:25344
	v_mov_b32_dpp v68, v25 row_ror:8 row_mask:0xf bank_mask:0xf
	v_mov_b32_dpp v69, v29 row_ror:8 row_mask:0xf bank_mask:0xf
	v_cvt_pk_bf16_f32 v70, v25, v68
	v_cvt_pk_bf16_f32 v71, v69, v29
	v_cndmask_b32_e32 v70, v70, v71, vcc
	ds_write_b32 v102, v70 offset:25476
	v_mov_b32_dpp v72, v26 row_ror:8 row_mask:0xf bank_mask:0xf
	v_mov_b32_dpp v73, v30 row_ror:8 row_mask:0xf bank_mask:0xf
	v_cvt_pk_bf16_f32 v74, v26, v72
	v_cvt_pk_bf16_f32 v75, v73, v30
	v_cndmask_b32_e32 v74, v74, v75, vcc
	ds_write_b32 v102, v74 offset:25608
	v_mov_b32_dpp v76, v27 row_ror:8 row_mask:0xf bank_mask:0xf
	v_mov_b32_dpp v77, v31 row_ror:8 row_mask:0xf bank_mask:0xf
	v_cvt_pk_bf16_f32 v78, v27, v76
	v_cvt_pk_bf16_f32 v79, v77, v31
	v_cndmask_b32_e32 v78, v78, v79, vcc
	ds_write_b32 v102, v78 offset:25740
	s_waitcnt lgkmcnt(0)
	s_barrier
	s_cmpk_ge_u32 s0, 0x580
	s_cselect_b32 s34, 1, 0
	s_cmpk_ge_u32 s0, 0x2c0
	s_cselect_b32 s35, 1, 0
	s_add_i32 s36, s34, s35
	s_mul_i32 s36, s36, 0x2c0
	s_sub_i32 s36, s0, s36
	s_sub_i32 s35, s35, s34
	s_mul_hi_u32 s37, s36, 0x2e8ba2f
	s_mul_i32 s38, s37, 0x58
	s_sub_i32 s38, s36, s38
	s_lshr_b32 s39, s36, 5
	s_and_b32 s40, s36, 31
	s_cmp_eq_u32 s34, 1
	s_cselect_b32 s37, s37, s39
	s_cselect_b32 s38, s38, s40
	s_cselect_b32 s56, s52, s50
	s_cselect_b32 s57, s53, s51
	s_mov_b32 s59, 0x40000
	s_cselect_b32 s59, 0xb0000, s59
	s_mov_b32 s90, 0x100000
	s_cselect_b32 s90, 0x160000, s90
	s_mov_b32 s41, 0x140000
	s_cselect_b32 s41, 0x210000, s41
	s_mov_b32 s39, 0x200000
	s_cselect_b32 s39, 0x2c0000, s39
	s_cselect_b64 s[28:29], -1, 0
	s_mul_i32 s39, s37, s39
	s_lshl_b32 s40, s38, 7
	s_add_u32 s39, s39, s40
	s_lshl_b32 s40, s35, 19
	s_add_u32 s39, s39, s40
	s_add_u32 s56, s56, s39
	s_addc_u32 s57, s57, 0
	v_cndmask_b32_e64 v107, v104, v105, s[28:29]
	v_add_u32_e32 v108, s59, v107
	v_add_u32_e32 v109, s90, v107
	v_add_u32_e32 v110, s41, v107
	ds_read_b32 v80, v103 offset:0
	ds_read_b32 v81, v103 offset:4
	ds_read_b32 v82, v103 offset:8
	ds_read_b32 v83, v103 offset:12
	ds_read_b32 v84, v103 offset:8448
	ds_read_b32 v85, v103 offset:8452
	ds_read_b32 v86, v103 offset:8456
	ds_read_b32 v87, v103 offset:8460
	ds_read_b32 v88, v103 offset:16896
	ds_read_b32 v89, v103 offset:16900
	ds_read_b32 v90, v103 offset:16904
	ds_read_b32 v91, v103 offset:16908
	ds_read_b32 v92, v103 offset:25344
	ds_read_b32 v93, v103 offset:25348
	ds_read_b32 v94, v103 offset:25352
	ds_read_b32 v95, v103 offset:25356
	s_waitcnt lgkmcnt(0)
	global_store_dwordx4 v107, v[80:83], s[56:57]
	global_store_dwordx4 v108, v[84:87], s[56:57]
	global_store_dwordx4 v109, v[88:91], s[56:57]
	global_store_dwordx4 v110, v[92:95], s[56:57]
	s_add_i32 s0, s0, s2
	s_cmp_ge_u32 s0, 1056
	s_cbranch_scc1 .Lfce_done
; __device__ __forceinline__ unsigned cvt_pk_bf16(float lo, float hi) { unsigned r; asm("v_cvt_pk_bf16_f32 %0, %1, %2" : "=v"(r) : "v"(lo), "v"(hi)); return r; }
; template <class SEL, class CTX>
; __device__ __forceinline__ void transpose_run(LAS unsigned char* lds, const CTX& ctx, int t0, int t1, int stride) {
;     ...
;         for (int q = 0; q < 4; ++q)
; #pragma unroll
;             for (int j = 0; j < 4; ++j) { const float lo = v[q][0][j], hi = v[q][1][j];
;                 const float recv = __shfl_xor((k & 1) ? lo : hi, 8);
;                 w[q][j] = (k & 1) ? cvt_pk_bf16(recv, hi) : cvt_pk_bf16(lo, recv); }
;         if (t + stride < t1) { TrDesc dn; int ltn; SEL::get(ctx, t + stride, dn, ltn); const int nktn = dn.K >> 6, ktn = ltn % nktn, ctn = ltn / nktn;
;             const float* s = dn.src + (size_t)(ktn * 64 + k) * dn.ldsrc + dn.c0 + ctn * 256 + n8;
; #pragma unroll
;             for (int q = 0; q < 4; ++q) { v[q][0] = *(const f32x4*)(s + q * 64); v[q][1] = *(const f32x4*)(s + q * 64 + 4); } }
; #pragma unroll
;         for (int q = 0; q < 4; ++q)
; #pragma unroll
;             for (int j = 0; j < 4; ++j) tl[(q * 64 + n8 + j + ((k & 1) ? 4 : 0)) * 33 + (k >> 1)] = w[q][j];
	s_add_i32 s33, s0, s2
	s_cmp_lt_u32 s33, 1056
	s_cselect_b32 s33, s33, s0
	s_cmpk_ge_u32 s33, 0x580
	s_cselect_b32 s34, 1, 0
	s_cmpk_ge_u32 s33, 0x2c0
	s_cselect_b32 s35, 1, 0
	s_add_i32 s36, s34, s35
	s_mul_i32 s36, s36, 0x2c0
	s_sub_i32 s36, s33, s36
	s_sub_i32 s35, s35, s34
	s_mul_hi_u32 s37, s36, 0x2e8ba2f
	s_mul_i32 s38, s37, 0x58
	s_sub_i32 s38, s36, s38
	s_lshr_b32 s39, s36, 5
	s_and_b32 s40, s36, 31
	s_cmp_eq_u32 s34, 1
	s_cselect_b32 s37, s37, s39
	s_cselect_b32 s38, s38, s40
	s_mov_b32 s58, 0x5800
	s_cselect_b32 s58, 0x2000, s58
	s_cselect_b32 s54, s48, s44
	s_cselect_b32 s55, s49, s45
	s_cmp_eq_u32 s35, 1
	s_cselect_b32 s54, s46, s54
	s_cselect_b32 s55, s47, s55
	s_lshl_b32 s39, s38, 6
	s_mul_i32 s39, s39, s58
	s_lshl_b32 s40, s37, 10
	s_add_u32 s39, s39, s40
	s_add_u32 s54, s54, s39
	s_addc_u32 s55, s55, 0
	v_mad_u32_u24 v106, v100, s58, v101
	global_load_dwordx4 v[0:3], v106, s[54:55]
	global_load_dwordx4 v[4:7], v106, s[54:55] offset:16
	global_load_dwordx4 v[8:11], v106, s[54:55] offset:256
	global_load_dwordx4 v[12:15], v106, s[54:55] offset:272
	global_load_dwordx4 v[16:19], v106, s[54:55] offset:512
	global_load_dwordx4 v[20:23], v106, s[54:55] offset:528
	global_load_dwordx4 v[24:27], v106, s[54:55] offset:768
	global_load_dwordx4 v[28:31], v106, s[54:55] offset:784
	s_waitcnt vmcnt(8)
	v_mov_b32_dpp v64, v32 row_ror:8 row_mask:0xf bank_mask:0xf
	v_mov_b32_dpp v65, v36 row_ror:8 row_mask:0xf bank_mask:0xf
	v_cvt_pk_bf16_f32 v66, v32, v64
	v_cvt_pk_bf16_f32 v67, v65, v36
	v_cndmask_b32_e32 v66, v66, v67, vcc
	ds_write_b32 v102, v66 offset:33792
	v_mov_b32_dpp v68, v33 row_ror:8 row_mask:0xf bank_mask:0xf
	v_mov_b32_dpp v69, v37 row_ror:8 row_mask:0xf bank_mask:0xf
	v_cvt_pk_bf16_f32 v70, v33, v68
	v_cvt_pk_bf16_f32 v71, v69, v37
	v_cndmask_b32_e32 v70, v70, v71, vcc
	ds_write_b32 v102, v70 offset:33924
	v_mov_b32_dpp v72, v34 row_ror:8 row_mask:0xf bank_mask:0xf
	v_mov_b32_dpp v73, v38 row_ror:8 row_mask:0xf bank_mask:0xf
	v_cvt_pk_bf16_f32 v74, v34, v72
	v_cvt_pk_bf16_f32 v75, v73, v38
	v_cndmask_b32_e32 v74, v74, v75, vcc
	ds_write_b32 v102, v74 offset:34056
	v_mov_b32_dpp v76, v35 row_ror:8 row_mask:0xf bank_mask:0xf
	v_mov_b32_dpp v77, v39 row_ror:8 row_mask:0xf bank_mask:0xf
	v_cvt_pk_bf16_f32 v78, v35, v76
	v_cvt_pk_bf16_f32 v79, v77, v39
	v_cndmask_b32_e32 v78, v78, v79, vcc
	ds_write_b32 v102, v78 offset:34188
	v_mov_b32_dpp v64, v40 row_ror:8 row_mask:0xf bank_mask:0xf
	v_mov_b32_dpp v65, v44 row_ror:8 row_mask:0xf bank_mask:0xf
	v_cvt_pk_bf16_f32 v66, v40, v64
	v_cvt_pk_bf16_f32 v67, v65, v44
	v_cndmask_b32_e32 v66, v66, v67, vcc
	ds_write_b32 v102, v66 offset:42240
	v_mov_b32_dpp v68, v41 row_ror:8 row_mask:0xf bank_mask:0xf
	v_mov_b32_dpp v69, v45 row_ror:8 row_mask:0xf bank_mask:0xf
	v_cvt_pk_bf16_f32 v70, v41, v68
	v_cvt_pk_bf16_f32 v71, v69, v45
	v_cndmask_b32_e32 v70, v70, v71, vcc
	ds_write_b32 v102, v70 offset:42372
	v_mov_b32_dpp v72, v42 row_ror:8 row_mask:0xf bank_mask:0xf
	v_mov_b32_dpp v73, v46 row_ror:8 row_mask:0xf bank_mask:0xf
	v_cvt_pk_bf16_f32 v74, v42, v72
	v_cvt_pk_bf16_f32 v75, v73, v46
	v_cndmask_b32_e32 v74, v74, v75, vcc
	ds_write_b32 v102, v74 offset:42504
	v_mov_b32_dpp v76, v43 row_ror:8 row_mask:0xf bank_mask:0xf
	v_mov_b32_dpp v77, v47 row_ror:8 row_mask:0xf bank_mask:0xf
	v_cvt_pk_bf16_f32 v78, v43, v76
	v_cvt_pk_bf16_f32 v79, v77, v47
	v_cndmask_b32_e32 v78, v78, v79, vcc
	ds_write_b32 v102, v78 offset:42636
	v_mov_b32_dpp v64, v48 row_ror:8 row_mask:0xf bank_mask:0xf
	v_mov_b32_dpp v65, v52 row_ror:8 row_mask:0xf bank_mask:0xf
	v_cvt_pk_bf16_f32 v66, v48, v64
	v_cvt_pk_bf16_f32 v67, v65, v52
	v_cndmask_b32_e32 v66, v66, v67, vcc
	ds_write_b32 v102, v66 offset:50688
	v_mov_b32_dpp v68, v49 row_ror:8 row_mask:0xf bank_mask:0xf
	v_mov_b32_dpp v69, v53 row_ror:8 row_mask:0xf bank_mask:0xf
	v_cvt_pk_bf16_f32 v70, v49, v68
	v_cvt_pk_bf16_f32 v71, v69, v53
	v_cndmask_b32_e32 v70, v70, v71, vcc
	ds_write_b32 v102, v70 offset:50820
	v_mov_b32_dpp v72, v50 row_ror:8 row_mask:0xf bank_mask:0xf
	v_mov_b32_dpp v73, v54 row_ror:8 row_mask:0xf bank_mask:0xf
	v_cvt_pk_bf16_f32 v74, v50, v72
	v_cvt_pk_bf16_f32 v75, v73, v54
	v_cndmask_b32_e32 v74, v74, v75, vcc
	ds_write_b32 v102, v74 offset:50952
	v_mov_b32_dpp v76, v51 row_ror:8 row_mask:0xf bank_mask:0xf
	v_mov_b32_dpp v77, v55 row_ror:8 row_mask:0xf bank_mask:0xf
	v_cvt_pk_bf16_f32 v78, v51, v76
	v_cvt_pk_bf16_f32 v79, v77, v55
	v_cndmask_b32_e32 v78, v78, v79, vcc
	ds_write_b32 v102, v78 offset:51084
	v_mov_b32_dpp v64, v56 row_ror:8 row_mask:0xf bank_mask:0xf
	v_mov_b32_dpp v65, v60 row_ror:8 row_mask:0xf bank_mask:0xf
	v_cvt_pk_bf16_f32 v66, v56, v64
	v_cvt_pk_bf16_f32 v67, v65, v60
	v_cndmask_b32_e32 v66, v66, v67, vcc
	ds_write_b32 v102, v66 offset:59136
	v_mov_b32_dpp v68, v57 row_ror:8 row_mask:0xf bank_mask:0xf
	v_mov_b32_dpp v69, v61 row_ror:8 row_mask:0xf bank_mask:0xf
	v_cvt_pk_bf16_f32 v70, v57, v68
	v_cvt_pk_bf16_f32 v71, v69, v61
	v_cndmask_b32_e32 v70, v70, v71, vcc
	ds_write_b32 v102, v70 offset:59268
	v_mov_b32_dpp v72, v58 row_ror:8 row_mask:0xf bank_mask:0xf
	v_mov_b32_dpp v73, v62 row_ror:8 row_mask:0xf bank_mask:0xf
	v_cvt_pk_bf16_f32 v74, v58, v72
	v_cvt_pk_bf16_f32 v75, v73, v62
	v_cndmask_b32_e32 v74, v74, v75, vcc
	ds_write_b32 v102, v74 offset:59400
	v_mov_b32_dpp v76, v59 row_ror:8 row_mask:0xf bank_mask:0xf
	v_mov_b32_dpp v77, v63 row_ror:8 row_mask:0xf bank_mask:0xf
	v_cvt_pk_bf16_f32 v78, v59, v76
	v_cvt_pk_bf16_f32 v79, v77, v63
	v_cndmask_b32_e32 v78, v78, v79, vcc
	ds_write_b32 v102, v78 offset:59532
	s_waitcnt lgkmcnt(0)
	s_barrier
; #define LAS __attribute__((address_space(3)))
; template <class SEL, class CTX>
; __device__ __forceinline__ void transpose_run(LAS unsigned char* lds, const CTX& ctx, int t0, int t1, int stride) {
;     ...
;         { const int n = tid >> 3, k8 = (tid & 7) * 8;
; #pragma unroll
;           for (int q = 0; q < 4; ++q) {
;               const LAS unsigned* p = tl + (q * 64 + n) * 33 + (k8 >> 1);
;               u32x4 ww; ww.x = p[0]; ww.y = p[1]; ww.z = p[2]; ww.w = p[3];
;               const int cc = ct * 256 + q * 64 + n;
;               const int drow = d.mode == 0 ? d.doff + cc : ((cc >> 7) * 256 + (cc & 127) + (d.mode == 2 ? 128 : 0));
;               *(u32x4*)(d.dst + (size_t)drow * d.K + kt * 64 + k8) = ww; } }
	s_cmpk_ge_u32 s0, 0x580
	s_cselect_b32 s34, 1, 0
	s_cmpk_ge_u32 s0, 0x2c0
	s_cselect_b32 s35, 1, 0
	s_add_i32 s36, s34, s35
	s_mul_i32 s36, s36, 0x2c0
	s_sub_i32 s36, s0, s36
	s_sub_i32 s35, s35, s34
	s_mul_hi_u32 s37, s36, 0x2e8ba2f
	s_mul_i32 s38, s37, 0x58
	s_sub_i32 s38, s36, s38
	s_lshr_b32 s39, s36, 5
	s_and_b32 s40, s36, 31
	s_cmp_eq_u32 s34, 1
	s_cselect_b32 s37, s37, s39
	s_cselect_b32 s38, s38, s40
	s_cselect_b32 s56, s52, s50
	s_cselect_b32 s57, s53, s51
	s_mov_b32 s59, 0x40000
	s_cselect_b32 s59, 0xb0000, s59
	s_mov_b32 s90, 0x100000
	s_cselect_b32 s90, 0x160000, s90
	s_mov_b32 s41, 0x140000
	s_cselect_b32 s41, 0x210000, s41
	s_mov_b32 s39, 0x200000
	s_cselect_b32 s39, 0x2c0000, s39
	s_cselect_b64 s[28:29], -1, 0
	s_mul_i32 s39, s37, s39
	s_lshl_b32 s40, s38, 7
	s_add_u32 s39, s39, s40
	s_lshl_b32 s40, s35, 19
	s_add_u32 s39, s39, s40
	s_add_u32 s56, s56, s39
	s_addc_u32 s57, s57, 0
	v_cndmask_b32_e64 v107, v104, v105, s[28:29]
	v_add_u32_e32 v108, s59, v107
	v_add_u32_e32 v109, s90, v107
	v_add_u32_e32 v110, s41, v107
	ds_read_b32 v80, v103 offset:33792
	ds_read_b32 v81, v103 offset:33796
	ds_read_b32 v82, v103 offset:33800
	ds_read_b32 v83, v103 offset:33804
	ds_read_b32 v84, v103 offset:42240
	ds_read_b32 v85, v103 offset:42244
	ds_read_b32 v86, v103 offset:42248
	ds_read_b32 v87, v103 offset:42252
	ds_read_b32 v88, v103 offset:50688
	ds_read_b32 v89, v103 offset:50692
	ds_read_b32 v90, v103 offset:50696
	ds_read_b32 v91, v103 offset:50700
	ds_read_b32 v92, v103 offset:59136
	ds_read_b32 v93, v103 offset:59140
	ds_read_b32 v94, v103 offset:59144
	ds_read_b32 v95, v103 offset:59148
	s_waitcnt lgkmcnt(0)
	global_store_dwordx4 v107, v[80:83], s[56:57]
	global_store_dwordx4 v108, v[84:87], s[56:57]
	global_store_dwordx4 v109, v[88:91], s[56:57]
	global_store_dwordx4 v110, v[92:95], s[56:57]
	s_add_i32 s0, s0, s2
	s_cmp_lt_u32 s0, 1056
	s_cbranch_scc1 .Lfce_loop
.Lfce_done:
	s_waitcnt vmcnt(0)
	v_readlane_b32 s0, v255, 24
	v_readlane_b32 s2, v255, 25
	v_readlane_b32 s28, v255, 26
	v_readlane_b32 s29, v255, 27
	v_readlane_b32 s33, v255, 28
	v_readlane_b32 s34, v255, 29
	v_readlane_b32 s35, v255, 30
	v_readlane_b32 s36, v255, 31
	v_readlane_b32 s37, v255, 32
	v_readlane_b32 s38, v255, 33
	v_readlane_b32 s39, v255, 34
	v_readlane_b32 s40, v255, 35
	v_readlane_b32 s41, v255, 36
	v_readlane_b32 s44, v255, 37
	v_readlane_b32 s45, v255, 38
	v_readlane_b32 s46, v255, 39
	v_readlane_b32 s47, v255, 44
	v_readlane_b32 s48, v255, 45
	v_readlane_b32 s49, v255, 46
	v_readlane_b32 s50, v255, 47
	v_readlane_b32 s51, v255, 48
	v_readlane_b32 s52, v255, 49
	v_readlane_b32 s53, v255, 50
	v_readlane_b32 s54, v255, 51
	v_readlane_b32 s55, v255, 52
	v_readlane_b32 s56, v255, 53
	v_readlane_b32 s57, v255, 54
	v_readlane_b32 s58, v255, 55
	v_readlane_b32 s59, v255, 56
	v_readlane_b32 s90, v255, 57
	v_readlane_b32 vcc_lo, v255, 58
	v_readlane_b32 vcc_hi, v255, 59
	s_nop 3

; #define LAS __attribute__((address_space(3)))
; __device__ __forceinline__ int tid_l() { int t = threadIdx.x; asm volatile("" : "+v"(t)); return t; }
; __device__ __forceinline__ unsigned cvt_pk_bf16(float lo, float hi) { unsigned r; asm("v_cvt_pk_bf16_f32 %0, %1, %2" : "=v"(r) : "v"(lo), "v"(hi)); return r; }
; template <class SEL, class CTX>
; __device__ __forceinline__ void transpose_run(LAS unsigned char* lds, const CTX& ctx, int t0, int t1, int stride) {
;     const int tid = tid_l();
;     LAS unsigned* tl = (LAS unsigned*)lds;
;     const int k = tid >> 3, n8 = (tid & 7) * 8;
;     f32x4 v[4][2];
;     TrDesc d; int lt;
;     if (t0 < t1) { SEL::get(ctx, t0, d, lt); const int nkt = d.K >> 6, kt = lt % nkt, ct = lt / nkt;
;         const float* s = d.src + (size_t)(kt * 64 + k) * d.ldsrc + d.c0 + ct * 256 + n8;
; #pragma unroll
;         for (int q = 0; q < 4; ++q) { v[q][0] = *(const f32x4*)(s + q * 64); v[q][1] = *(const f32x4*)(s + q * 64 + 4); } }
;     for (int t = t0; t < t1; t += stride) {
;         SEL::get(ctx, t, d, lt);
;         const int nkt = d.K >> 6, kt = lt % nkt, ct = lt / nkt;
;         unsigned w[4][4];
; #pragma unroll
;         for (int q = 0; q < 4; ++q)
; #pragma unroll
;             for (int j = 0; j < 4; ++j) { const float lo = v[q][0][j], hi = v[q][1][j];
;                 const float recv = __shfl_xor((k & 1) ? lo : hi, 8);
;                 w[q][j] = (k & 1) ? cvt_pk_bf16(recv, hi) : cvt_pk_bf16(lo, recv); }
;         if (t + stride < t1) { TrDesc dn; int ltn; SEL::get(ctx, t + stride, dn, ltn); const int nktn = dn.K >> 6, ktn = ltn % nktn, ctn = ltn / nktn;
;             const float* s = dn.src + (size_t)(ktn * 64 + k) * dn.ldsrc + dn.c0 + ctn * 256 + n8;
; #pragma unroll
;             for (int q = 0; q < 4; ++q) { v[q][0] = *(const f32x4*)(s + q * 64); v[q][1] = *(const f32x4*)(s + q * 64 + 4); } }
.LBB0_1000:
	s_cmp_lt_i32 s65, 32
	s_cbranch_scc1 .LBB0_1084
	v_writelane_b32 v255, s0, 24
	v_writelane_b32 v255, s2, 25
	v_writelane_b32 v255, s28, 26
	v_writelane_b32 v255, s29, 27
	v_writelane_b32 v255, s33, 28
	v_writelane_b32 v255, s34, 29
	v_writelane_b32 v255, s35, 30
	v_writelane_b32 v255, s36, 31
	v_writelane_b32 v255, s37, 32
	v_writelane_b32 v255, s38, 33
	v_writelane_b32 v255, s39, 34
	v_writelane_b32 v255, s40, 35
	v_writelane_b32 v255, s41, 36
	v_writelane_b32 v255, s44, 37
	v_writelane_b32 v255, s45, 38
	v_writelane_b32 v255, s46, 39
	v_writelane_b32 v255, s47, 44
	v_writelane_b32 v255, s48, 45
	v_writelane_b32 v255, s49, 46
	v_writelane_b32 v255, s50, 47
	v_writelane_b32 v255, s51, 48
	v_writelane_b32 v255, s52, 49
	v_writelane_b32 v255, s53, 50
	v_writelane_b32 v255, s54, 51
	v_writelane_b32 v255, s55, 52
	v_writelane_b32 v255, s56, 53
	v_writelane_b32 v255, s57, 54
	v_writelane_b32 v255, s58, 55
	v_writelane_b32 v255, s59, 56
	v_writelane_b32 v255, s90, 57
	v_writelane_b32 v255, vcc_lo, 58
	v_writelane_b32 v255, vcc_hi, 59
	s_sub_i32 s0, s65, 32
	s_add_i32 s0, s0, 1056
	s_sub_i32 s2, s31, 32
	s_mul_i32 s28, s30, 0x2c00000
	v_readlane_b32 s44, v253, 28
	v_readlane_b32 s45, v253, 29
	v_readlane_b32 s46, v253, 30
	v_readlane_b32 s47, v253, 31
	v_readlane_b32 s48, v253, 32
	v_readlane_b32 s49, v253, 33
	s_nop 3
	s_add_u32 s44, s44, s28
	s_addc_u32 s45, s45, 0
	s_add_u32 s46, s46, s28
	s_addc_u32 s47, s47, 0
	s_add_u32 s48, s48, s28
	s_addc_u32 s49, s49, 0
	s_add_u32 s50, s22, 0x1650000
	s_addc_u32 s51, s23, 0
	s_add_u32 s52, s22, 0x4250000
	s_addc_u32 s53, s23, 0
	v_lshrrev_b32_e32 v100, 3, v175
	v_and_b32_e32 v96, 7, v175
	v_lshlrev_b32_e32 v101, 5, v96
	v_and_b32_e32 v97, 1, v100
	v_cmp_ne_u32_e32 vcc, 0, v97
	v_lshlrev_b32_e32 v98, 3, v96
	v_lshl_add_u32 v98, v97, 2, v98
	v_mul_u32_u24_e32 v98, 33, v98
	v_lshrrev_b32_e32 v99, 1, v100
	v_add_u32_e32 v98, v98, v99
	v_lshlrev_b32_e32 v102, 2, v98
	v_mul_u32_u24_e32 v98, 33, v100
	v_lshl_add_u32 v98, v96, 2, v98
	v_lshlrev_b32_e32 v103, 2, v98
	v_lshlrev_b32_e32 v99, 4, v96
	v_lshl_add_u32 v104, v100, 12, v99
	v_mul_u32_u24_e32 v98, 0x2c00, v100
	v_add_u32_e32 v105, v98, v99
	s_mov_b32 s33, s0
	s_cmpk_ge_u32 s33, 0x580
	s_cselect_b32 s34, 1, 0
	s_cmpk_ge_u32 s33, 0x2c0
	s_cselect_b32 s35, 1, 0
	s_add_i32 s36, s34, s35
	s_mul_i32 s36, s36, 0x2c0
	s_sub_i32 s36, s33, s36
	s_sub_i32 s35, s35, s34
	s_mul_hi_u32 s37, s36, 0x2e8ba2f
	s_mul_i32 s38, s37, 0x58
	s_sub_i32 s38, s36, s38
	s_lshr_b32 s39, s36, 5
	s_and_b32 s40, s36, 31
	s_cmp_eq_u32 s34, 1
	s_cselect_b32 s37, s37, s39
	s_cselect_b32 s38, s38, s40
	s_mov_b32 s58, 0x5800
	s_cselect_b32 s58, 0x2000, s58
	s_cselect_b32 s54, s48, s44
	s_cselect_b32 s55, s49, s45
	s_cmp_eq_u32 s35, 1
	s_cselect_b32 s54, s46, s54
	s_cselect_b32 s55, s47, s55
	s_lshl_b32 s39, s38, 6
	s_mul_i32 s39, s39, s58
	s_lshl_b32 s40, s37, 10
	s_add_u32 s39, s39, s40
	s_add_u32 s54, s54, s39
	s_addc_u32 s55, s55, 0
	v_mad_u32_u24 v106, v100, s58, v101
	global_load_dwordx4 v[0:3], v106, s[54:55]
	global_load_dwordx4 v[4:7], v106, s[54:55] offset:16
	global_load_dwordx4 v[8:11], v106, s[54:55] offset:256
	global_load_dwordx4 v[12:15], v106, s[54:55] offset:272
	global_load_dwordx4 v[16:19], v106, s[54:55] offset:512
	global_load_dwordx4 v[20:23], v106, s[54:55] offset:528
	global_load_dwordx4 v[24:27], v106, s[54:55] offset:768
	global_load_dwordx4 v[28:31], v106, s[54:55] offset:784
.Lfcf_loop:
	s_add_i32 s33, s0, s2
	s_cmp_lt_u32 s33, 2112
	s_cselect_b32 s33, s33, s0
	s_cmpk_ge_u32 s33, 0x580
	s_cselect_b32 s34, 1, 0
	s_cmpk_ge_u32 s33, 0x2c0
	s_cselect_b32 s35, 1, 0
	s_add_i32 s36, s34, s35
	s_mul_i32 s36, s36, 0x2c0
	s_sub_i32 s36, s33, s36
	s_sub_i32 s35, s35, s34
	s_mul_hi_u32 s37, s36, 0x2e8ba2f
	s_mul_i32 s38, s37, 0x58
	s_sub_i32 s38, s36, s38
	s_lshr_b32 s39, s36, 5
	s_and_b32 s40, s36, 31
	s_cmp_eq_u32 s34, 1
	s_cselect_b32 s37, s37, s39
	s_cselect_b32 s38, s38, s40
	s_mov_b32 s58, 0x5800
	s_cselect_b32 s58, 0x2000, s58
	s_cselect_b32 s54, s48, s44
	s_cselect_b32 s55, s49, s45
	s_cmp_eq_u32 s35, 1
	s_cselect_b32 s54, s46, s54
	s_cselect_b32 s55, s47, s55
	s_lshl_b32 s39, s38, 6
	s_mul_i32 s39, s39, s58
	s_lshl_b32 s40, s37, 10
	s_add_u32 s39, s39, s40
	s_add_u32 s54, s54, s39
	s_addc_u32 s55, s55, 0
	v_mad_u32_u24 v106, v100, s58, v101
	global_load_dwordx4 v[32:35], v106, s[54:55]
	global_load_dwordx4 v[36:39], v106, s[54:55] offset:16
	global_load_dwordx4 v[40:43], v106, s[54:55] offset:256
	global_load_dwordx4 v[44:47], v106, s[54:55] offset:272
	global_load_dwordx4 v[48:51], v106, s[54:55] offset:512
	global_load_dwordx4 v[52:55], v106, s[54:55] offset:528
	global_load_dwordx4 v[56:59], v106, s[54:55] offset:768
	global_load_dwordx4 v[60:63], v106, s[54:55] offset:784
	s_waitcnt vmcnt(8)
; #define LAS __attribute__((address_space(3)))
; __device__ __forceinline__ unsigned cvt_pk_bf16(float lo, float hi) { unsigned r; asm("v_cvt_pk_bf16_f32 %0, %1, %2" : "=v"(r) : "v"(lo), "v"(hi)); return r; }
; template <class SEL, class CTX>
; __device__ __forceinline__ void transpose_run(LAS unsigned char* lds, const CTX& ctx, int t0, int t1, int stride) {
;     ...
;         for (int q = 0; q < 4; ++q)
; #pragma unroll
;             for (int j = 0; j < 4; ++j) { const float lo = v[q][0][j], hi = v[q][1][j];
;                 const float recv = __shfl_xor((k & 1) ? lo : hi, 8);
;                 w[q][j] = (k & 1) ? cvt_pk_bf16(recv, hi) : cvt_pk_bf16(lo, recv); }
;         if (t + stride < t1) { TrDesc dn; int ltn; SEL::get(ctx, t + stride, dn, ltn); const int nktn = dn.K >> 6, ktn = ltn % nktn, ctn = ltn / nktn;
;             const float* s = dn.src + (size_t)(ktn * 64 + k) * dn.ldsrc + dn.c0 + ctn * 256 + n8;
; #pragma unroll
;             for (int q = 0; q < 4; ++q) { v[q][0] = *(const f32x4*)(s + q * 64); v[q][1] = *(const f32x4*)(s + q * 64 + 4); } }
; #pragma unroll
;         for (int q = 0; q < 4; ++q)
; #pragma unroll
;             for (int j = 0; j < 4; ++j) tl[(q * 64 + n8 + j + ((k & 1) ? 4 : 0)) * 33 + (k >> 1)] = w[q][j];
;         __syncthreads();
;         { const int n = tid >> 3, k8 = (tid & 7) * 8;
; #pragma unroll
;           for (int q = 0; q < 4; ++q) {
;               const LAS unsigned* p = tl + (q * 64 + n) * 33 + (k8 >> 1);
;               u32x4 ww; ww.x = p[0]; ww.y = p[1]; ww.z = p[2]; ww.w = p[3];
;               const int cc = ct * 256 + q * 64 + n;
;               const int drow = d.mode == 0 ? d.doff + cc : ((cc >> 7) * 256 + (cc & 127) + (d.mode == 2 ? 128 : 0));
;               *(u32x4*)(d.dst + (size_t)drow * d.K + kt * 64 + k8) = ww; } }
	v_mov_b32_dpp v64, v0 row_ror:8 row_mask:0xf bank_mask:0xf
	v_mov_b32_dpp v65, v4 row_ror:8 row_mask:0xf bank_mask:0xf
	v_cvt_pk_bf16_f32 v66, v0, v64
	v_cvt_pk_bf16_f32 v67, v65, v4
	v_cndmask_b32_e32 v66, v66, v67, vcc
	ds_write_b32 v102, v66 offset:0
	v_mov_b32_dpp v68, v1 row_ror:8 row_mask:0xf bank_mask:0xf
	v_mov_b32_dpp v69, v5 row_ror:8 row_mask:0xf bank_mask:0xf
	v_cvt_pk_bf16_f32 v70, v1, v68
	v_cvt_pk_bf16_f32 v71, v69, v5
	v_cndmask_b32_e32 v70, v70, v71, vcc
	ds_write_b32 v102, v70 offset:132
	v_mov_b32_dpp v72, v2 row_ror:8 row_mask:0xf bank_mask:0xf
	v_mov_b32_dpp v73, v6 row_ror:8 row_mask:0xf bank_mask:0xf
	v_cvt_pk_bf16_f32 v74, v2, v72
	v_cvt_pk_bf16_f32 v75, v73, v6
	v_cndmask_b32_e32 v74, v74, v75, vcc
	ds_write_b32 v102, v74 offset:264
	v_mov_b32_dpp v76, v3 row_ror:8 row_mask:0xf bank_mask:0xf
	v_mov_b32_dpp v77, v7 row_ror:8 row_mask:0xf bank_mask:0xf
	v_cvt_pk_bf16_f32 v78, v3, v76
	v_cvt_pk_bf16_f32 v79, v77, v7
	v_cndmask_b32_e32 v78, v78, v79, vcc
	ds_write_b32 v102, v78 offset:396
	v_mov_b32_dpp v64, v8 row_ror:8 row_mask:0xf bank_mask:0xf
	v_mov_b32_dpp v65, v12 row_ror:8 row_mask:0xf bank_mask:0xf
	v_cvt_pk_bf16_f32 v66, v8, v64
	v_cvt_pk_bf16_f32 v67, v65, v12
	v_cndmask_b32_e32 v66, v66, v67, vcc
	ds_write_b32 v102, v66 offset:8448
	v_mov_b32_dpp v68, v9 row_ror:8 row_mask:0xf bank_mask:0xf
	v_mov_b32_dpp v69, v13 row_ror:8 row_mask:0xf bank_mask:0xf
	v_cvt_pk_bf16_f32 v70, v9, v68
	v_cvt_pk_bf16_f32 v71, v69, v13
	v_cndmask_b32_e32 v70, v70, v71, vcc
	ds_write_b32 v102, v70 offset:8580
	v_mov_b32_dpp v72, v10 row_ror:8 row_mask:0xf bank_mask:0xf
	v_mov_b32_dpp v73, v14 row_ror:8 row_mask:0xf bank_mask:0xf
	v_cvt_pk_bf16_f32 v74, v10, v72
	v_cvt_pk_bf16_f32 v75, v73, v14
	v_cndmask_b32_e32 v74, v74, v75, vcc
	ds_write_b32 v102, v74 offset:8712
	v_mov_b32_dpp v76, v11 row_ror:8 row_mask:0xf bank_mask:0xf
	v_mov_b32_dpp v77, v15 row_ror:8 row_mask:0xf bank_mask:0xf
	v_cvt_pk_bf16_f32 v78, v11, v76
	v_cvt_pk_bf16_f32 v79, v77, v15
	v_cndmask_b32_e32 v78, v78, v79, vcc
	ds_write_b32 v102, v78 offset:8844
	v_mov_b32_dpp v64, v16 row_ror:8 row_mask:0xf bank_mask:0xf
	v_mov_b32_dpp v65, v20 row_ror:8 row_mask:0xf bank_mask:0xf
	v_cvt_pk_bf16_f32 v66, v16, v64
	v_cvt_pk_bf16_f32 v67, v65, v20
	v_cndmask_b32_e32 v66, v66, v67, vcc
	ds_write_b32 v102, v66 offset:16896
	v_mov_b32_dpp v68, v17 row_ror:8 row_mask:0xf bank_mask:0xf
	v_mov_b32_dpp v69, v21 row_ror:8 row_mask:0xf bank_mask:0xf
	v_cvt_pk_bf16_f32 v70, v17, v68
	v_cvt_pk_bf16_f32 v71, v69, v21
	v_cndmask_b32_e32 v70, v70, v71, vcc
	ds_write_b32 v102, v70 offset:17028
	v_mov_b32_dpp v72, v18 row_ror:8 row_mask:0xf bank_mask:0xf
	v_mov_b32_dpp v73, v22 row_ror:8 row_mask:0xf bank_mask:0xf
	v_cvt_pk_bf16_f32 v74, v18, v72
	v_cvt_pk_bf16_f32 v75, v73, v22
	v_cndmask_b32_e32 v74, v74, v75, vcc
	ds_write_b32 v102, v74 offset:17160
	v_mov_b32_dpp v76, v19 row_ror:8 row_mask:0xf bank_mask:0xf
	v_mov_b32_dpp v77, v23 row_ror:8 row_mask:0xf bank_mask:0xf
	v_cvt_pk_bf16_f32 v78, v19, v76
	v_cvt_pk_bf16_f32 v79, v77, v23
	v_cndmask_b32_e32 v78, v78, v79, vcc
	ds_write_b32 v102, v78 offset:17292
	v_mov_b32_dpp v64, v24 row_ror:8 row_mask:0xf bank_mask:0xf
	v_mov_b32_dpp v65, v28 row_ror:8 row_mask:0xf bank_mask:0xf
	v_cvt_pk_bf16_f32 v66, v24, v64
	v_cvt_pk_bf16_f32 v67, v65, v28
	v_cndmask_b32_e32 v66, v66, v67, vcc
	ds_write_b32 v102, v66 offset:25344
	v_mov_b32_dpp v68, v25 row_ror:8 row_mask:0xf bank_mask:0xf
	v_mov_b32_dpp v69, v29 row_ror:8 row_mask:0xf bank_mask:0xf
	v_cvt_pk_bf16_f32 v70, v25, v68
	v_cvt_pk_bf16_f32 v71, v69, v29
	v_cndmask_b32_e32 v70, v70, v71, vcc
	ds_write_b32 v102, v70 offset:25476
	v_mov_b32_dpp v72, v26 row_ror:8 row_mask:0xf bank_mask:0xf
	v_mov_b32_dpp v73, v30 row_ror:8 row_mask:0xf bank_mask:0xf
	v_cvt_pk_bf16_f32 v74, v26, v72
	v_cvt_pk_bf16_f32 v75, v73, v30
	v_cndmask_b32_e32 v74, v74, v75, vcc
	ds_write_b32 v102, v74 offset:25608
	v_mov_b32_dpp v76, v27 row_ror:8 row_mask:0xf bank_mask:0xf
	v_mov_b32_dpp v77, v31 row_ror:8 row_mask:0xf bank_mask:0xf
	v_cvt_pk_bf16_f32 v78, v27, v76
	v_cvt_pk_bf16_f32 v79, v77, v31
	v_cndmask_b32_e32 v78, v78, v79, vcc
	ds_write_b32 v102, v78 offset:25740
	s_waitcnt lgkmcnt(0)
	s_barrier
	s_cmpk_ge_u32 s0, 0x580
	s_cselect_b32 s34, 1, 0
	s_cmpk_ge_u32 s0, 0x2c0
	s_cselect_b32 s35, 1, 0
	s_add_i32 s36, s34, s35
	s_mul_i32 s36, s36, 0x2c0
	s_sub_i32 s36, s0, s36
	s_sub_i32 s35, s35, s34
	s_mul_hi_u32 s37, s36, 0x2e8ba2f
	s_mul_i32 s38, s37, 0x58
	s_sub_i32 s38, s36, s38
	s_lshr_b32 s39, s36, 5
	s_and_b32 s40, s36, 31
	s_cmp_eq_u32 s34, 1
	s_cselect_b32 s37, s37, s39
	s_cselect_b32 s38, s38, s40
	s_cselect_b32 s56, s52, s50
	s_cselect_b32 s57, s53, s51
	s_mov_b32 s59, 0x40000
	s_cselect_b32 s59, 0xb0000, s59
	s_mov_b32 s90, 0x100000
	s_cselect_b32 s90, 0x160000, s90
	s_mov_b32 s41, 0x140000
	s_cselect_b32 s41, 0x210000, s41
	s_mov_b32 s39, 0x200000
	s_cselect_b32 s39, 0x2c0000, s39
	s_cselect_b64 s[28:29], -1, 0
	s_mul_i32 s39, s37, s39
	s_lshl_b32 s40, s38, 7
	s_add_u32 s39, s39, s40
	s_lshl_b32 s40, s35, 19
	s_add_u32 s39, s39, s40
	s_add_u32 s56, s56, s39
	s_addc_u32 s57, s57, 0
	v_cndmask_b32_e64 v107, v104, v105, s[28:29]
	v_add_u32_e32 v108, s59, v107
	v_add_u32_e32 v109, s90, v107
	v_add_u32_e32 v110, s41, v107
	ds_read_b32 v80, v103 offset:0
	ds_read_b32 v81, v103 offset:4
	ds_read_b32 v82, v103 offset:8
	ds_read_b32 v83, v103 offset:12
	ds_read_b32 v84, v103 offset:8448
	ds_read_b32 v85, v103 offset:8452
	ds_read_b32 v86, v103 offset:8456
	ds_read_b32 v87, v103 offset:8460
	ds_read_b32 v88, v103 offset:16896
	ds_read_b32 v89, v103 offset:16900
	ds_read_b32 v90, v103 offset:16904
	ds_read_b32 v91, v103 offset:16908
	ds_read_b32 v92, v103 offset:25344
	ds_read_b32 v93, v103 offset:25348
	ds_read_b32 v94, v103 offset:25352
	ds_read_b32 v95, v103 offset:25356
	s_waitcnt lgkmcnt(0)
	global_store_dwordx4 v107, v[80:83], s[56:57]
	global_store_dwordx4 v108, v[84:87], s[56:57]
	global_store_dwordx4 v109, v[88:91], s[56:57]
	global_store_dwordx4 v110, v[92:95], s[56:57]
	s_add_i32 s0, s0, s2
	s_cmp_ge_u32 s0, 2112
	s_cbranch_scc1 .Lfcf_done
; __device__ __forceinline__ unsigned cvt_pk_bf16(float lo, float hi) { unsigned r; asm("v_cvt_pk_bf16_f32 %0, %1, %2" : "=v"(r) : "v"(lo), "v"(hi)); return r; }
; template <class SEL, class CTX>
; __device__ __forceinline__ void transpose_run(LAS unsigned char* lds, const CTX& ctx, int t0, int t1, int stride) {
;     ...
;         for (int q = 0; q < 4; ++q)
; #pragma unroll
;             for (int j = 0; j < 4; ++j) { const float lo = v[q][0][j], hi = v[q][1][j];
;                 const float recv = __shfl_xor((k & 1) ? lo : hi, 8);
;                 w[q][j] = (k & 1) ? cvt_pk_bf16(recv, hi) : cvt_pk_bf16(lo, recv); }
;         if (t + stride < t1) { TrDesc dn; int ltn; SEL::get(ctx, t + stride, dn, ltn); const int nktn = dn.K >> 6, ktn = ltn % nktn, ctn = ltn / nktn;
;             const float* s = dn.src + (size_t)(ktn * 64 + k) * dn.ldsrc + dn.c0 + ctn * 256 + n8;
; #pragma unroll
;             for (int q = 0; q < 4; ++q) { v[q][0] = *(const f32x4*)(s + q * 64); v[q][1] = *(const f32x4*)(s + q * 64 + 4); } }
; #pragma unroll
;         for (int q = 0; q < 4; ++q)
; #pragma unroll
;             for (int j = 0; j < 4; ++j) tl[(q * 64 + n8 + j + ((k & 1) ? 4 : 0)) * 33 + (k >> 1)] = w[q][j];
	s_add_i32 s33, s0, s2
	s_cmp_lt_u32 s33, 2112
	s_cselect_b32 s33, s33, s0
	s_cmpk_ge_u32 s33, 0x580
	s_cselect_b32 s34, 1, 0
	s_cmpk_ge_u32 s33, 0x2c0
	s_cselect_b32 s35, 1, 0
	s_add_i32 s36, s34, s35
	s_mul_i32 s36, s36, 0x2c0
	s_sub_i32 s36, s33, s36
	s_sub_i32 s35, s35, s34
	s_mul_hi_u32 s37, s36, 0x2e8ba2f
	s_mul_i32 s38, s37, 0x58
	s_sub_i32 s38, s36, s38
	s_lshr_b32 s39, s36, 5
	s_and_b32 s40, s36, 31
	s_cmp_eq_u32 s34, 1
	s_cselect_b32 s37, s37, s39
	s_cselect_b32 s38, s38, s40
	s_mov_b32 s58, 0x5800
	s_cselect_b32 s58, 0x2000, s58
	s_cselect_b32 s54, s48, s44
	s_cselect_b32 s55, s49, s45
	s_cmp_eq_u32 s35, 1
	s_cselect_b32 s54, s46, s54
	s_cselect_b32 s55, s47, s55
	s_lshl_b32 s39, s38, 6
	s_mul_i32 s39, s39, s58
	s_lshl_b32 s40, s37, 10
	s_add_u32 s39, s39, s40
	s_add_u32 s54, s54, s39
	s_addc_u32 s55, s55, 0
	v_mad_u32_u24 v106, v100, s58, v101
	global_load_dwordx4 v[0:3], v106, s[54:55]
	global_load_dwordx4 v[4:7], v106, s[54:55] offset:16
	global_load_dwordx4 v[8:11], v106, s[54:55] offset:256
	global_load_dwordx4 v[12:15], v106, s[54:55] offset:272
	global_load_dwordx4 v[16:19], v106, s[54:55] offset:512
	global_load_dwordx4 v[20:23], v106, s[54:55] offset:528
	global_load_dwordx4 v[24:27], v106, s[54:55] offset:768
	global_load_dwordx4 v[28:31], v106, s[54:55] offset:784
	s_waitcnt vmcnt(8)
	v_mov_b32_dpp v64, v32 row_ror:8 row_mask:0xf bank_mask:0xf
	v_mov_b32_dpp v65, v36 row_ror:8 row_mask:0xf bank_mask:0xf
	v_cvt_pk_bf16_f32 v66, v32, v64
	v_cvt_pk_bf16_f32 v67, v65, v36
	v_cndmask_b32_e32 v66, v66, v67, vcc
	ds_write_b32 v102, v66 offset:33792
	v_mov_b32_dpp v68, v33 row_ror:8 row_mask:0xf bank_mask:0xf
	v_mov_b32_dpp v69, v37 row_ror:8 row_mask:0xf bank_mask:0xf
	v_cvt_pk_bf16_f32 v70, v33, v68
	v_cvt_pk_bf16_f32 v71, v69, v37
	v_cndmask_b32_e32 v70, v70, v71, vcc
	ds_write_b32 v102, v70 offset:33924
	v_mov_b32_dpp v72, v34 row_ror:8 row_mask:0xf bank_mask:0xf
	v_mov_b32_dpp v73, v38 row_ror:8 row_mask:0xf bank_mask:0xf
	v_cvt_pk_bf16_f32 v74, v34, v72
	v_cvt_pk_bf16_f32 v75, v73, v38
	v_cndmask_b32_e32 v74, v74, v75, vcc
	ds_write_b32 v102, v74 offset:34056
	v_mov_b32_dpp v76, v35 row_ror:8 row_mask:0xf bank_mask:0xf
	v_mov_b32_dpp v77, v39 row_ror:8 row_mask:0xf bank_mask:0xf
	v_cvt_pk_bf16_f32 v78, v35, v76
	v_cvt_pk_bf16_f32 v79, v77, v39
	v_cndmask_b32_e32 v78, v78, v79, vcc
	ds_write_b32 v102, v78 offset:34188
	v_mov_b32_dpp v64, v40 row_ror:8 row_mask:0xf bank_mask:0xf
	v_mov_b32_dpp v65, v44 row_ror:8 row_mask:0xf bank_mask:0xf
	v_cvt_pk_bf16_f32 v66, v40, v64
	v_cvt_pk_bf16_f32 v67, v65, v44
	v_cndmask_b32_e32 v66, v66, v67, vcc
	ds_write_b32 v102, v66 offset:42240
	v_mov_b32_dpp v68, v41 row_ror:8 row_mask:0xf bank_mask:0xf
	v_mov_b32_dpp v69, v45 row_ror:8 row_mask:0xf bank_mask:0xf
	v_cvt_pk_bf16_f32 v70, v41, v68
	v_cvt_pk_bf16_f32 v71, v69, v45
	v_cndmask_b32_e32 v70, v70, v71, vcc
	ds_write_b32 v102, v70 offset:42372
	v_mov_b32_dpp v72, v42 row_ror:8 row_mask:0xf bank_mask:0xf
	v_mov_b32_dpp v73, v46 row_ror:8 row_mask:0xf bank_mask:0xf
	v_cvt_pk_bf16_f32 v74, v42, v72
	v_cvt_pk_bf16_f32 v75, v73, v46
	v_cndmask_b32_e32 v74, v74, v75, vcc
	ds_write_b32 v102, v74 offset:42504
	v_mov_b32_dpp v76, v43 row_ror:8 row_mask:0xf bank_mask:0xf
	v_mov_b32_dpp v77, v47 row_ror:8 row_mask:0xf bank_mask:0xf
	v_cvt_pk_bf16_f32 v78, v43, v76
	v_cvt_pk_bf16_f32 v79, v77, v47
	v_cndmask_b32_e32 v78, v78, v79, vcc
	ds_write_b32 v102, v78 offset:42636
	v_mov_b32_dpp v64, v48 row_ror:8 row_mask:0xf bank_mask:0xf
	v_mov_b32_dpp v65, v52 row_ror:8 row_mask:0xf bank_mask:0xf
	v_cvt_pk_bf16_f32 v66, v48, v64
	v_cvt_pk_bf16_f32 v67, v65, v52
	v_cndmask_b32_e32 v66, v66, v67, vcc
	ds_write_b32 v102, v66 offset:50688
	v_mov_b32_dpp v68, v49 row_ror:8 row_mask:0xf bank_mask:0xf
	v_mov_b32_dpp v69, v53 row_ror:8 row_mask:0xf bank_mask:0xf
	v_cvt_pk_bf16_f32 v70, v49, v68
	v_cvt_pk_bf16_f32 v71, v69, v53
	v_cndmask_b32_e32 v70, v70, v71, vcc
	ds_write_b32 v102, v70 offset:50820
	v_mov_b32_dpp v72, v50 row_ror:8 row_mask:0xf bank_mask:0xf
	v_mov_b32_dpp v73, v54 row_ror:8 row_mask:0xf bank_mask:0xf
	v_cvt_pk_bf16_f32 v74, v50, v72
	v_cvt_pk_bf16_f32 v75, v73, v54
	v_cndmask_b32_e32 v74, v74, v75, vcc
	ds_write_b32 v102, v74 offset:50952
	v_mov_b32_dpp v76, v51 row_ror:8 row_mask:0xf bank_mask:0xf
	v_mov_b32_dpp v77, v55 row_ror:8 row_mask:0xf bank_mask:0xf
	v_cvt_pk_bf16_f32 v78, v51, v76
	v_cvt_pk_bf16_f32 v79, v77, v55
	v_cndmask_b32_e32 v78, v78, v79, vcc
	ds_write_b32 v102, v78 offset:51084
	v_mov_b32_dpp v64, v56 row_ror:8 row_mask:0xf bank_mask:0xf
	v_mov_b32_dpp v65, v60 row_ror:8 row_mask:0xf bank_mask:0xf
	v_cvt_pk_bf16_f32 v66, v56, v64
	v_cvt_pk_bf16_f32 v67, v65, v60
	v_cndmask_b32_e32 v66, v66, v67, vcc
	ds_write_b32 v102, v66 offset:59136
	v_mov_b32_dpp v68, v57 row_ror:8 row_mask:0xf bank_mask:0xf
	v_mov_b32_dpp v69, v61 row_ror:8 row_mask:0xf bank_mask:0xf
	v_cvt_pk_bf16_f32 v70, v57, v68
	v_cvt_pk_bf16_f32 v71, v69, v61
	v_cndmask_b32_e32 v70, v70, v71, vcc
	ds_write_b32 v102, v70 offset:59268
	v_mov_b32_dpp v72, v58 row_ror:8 row_mask:0xf bank_mask:0xf
	v_mov_b32_dpp v73, v62 row_ror:8 row_mask:0xf bank_mask:0xf
	v_cvt_pk_bf16_f32 v74, v58, v72
	v_cvt_pk_bf16_f32 v75, v73, v62
	v_cndmask_b32_e32 v74, v74, v75, vcc
	ds_write_b32 v102, v74 offset:59400
	v_mov_b32_dpp v76, v59 row_ror:8 row_mask:0xf bank_mask:0xf
	v_mov_b32_dpp v77, v63 row_ror:8 row_mask:0xf bank_mask:0xf
	v_cvt_pk_bf16_f32 v78, v59, v76
	v_cvt_pk_bf16_f32 v79, v77, v63
	v_cndmask_b32_e32 v78, v78, v79, vcc
	ds_write_b32 v102, v78 offset:59532
	s_waitcnt lgkmcnt(0)
	s_barrier
; #define LAS __attribute__((address_space(3)))
; template <class SEL, class CTX>
; __device__ __forceinline__ void transpose_run(LAS unsigned char* lds, const CTX& ctx, int t0, int t1, int stride) {
;     ...
;         { const int n = tid >> 3, k8 = (tid & 7) * 8;
; #pragma unroll
;           for (int q = 0; q < 4; ++q) {
;               const LAS unsigned* p = tl + (q * 64 + n) * 33 + (k8 >> 1);
;               u32x4 ww; ww.x = p[0]; ww.y = p[1]; ww.z = p[2]; ww.w = p[3];
;               const int cc = ct * 256 + q * 64 + n;
;               const int drow = d.mode == 0 ? d.doff + cc : ((cc >> 7) * 256 + (cc & 127) + (d.mode == 2 ? 128 : 0));
;               *(u32x4*)(d.dst + (size_t)drow * d.K + kt * 64 + k8) = ww; } }
	s_cmpk_ge_u32 s0, 0x580
	s_cselect_b32 s34, 1, 0
	s_cmpk_ge_u32 s0, 0x2c0
	s_cselect_b32 s35, 1, 0
	s_add_i32 s36, s34, s35
	s_mul_i32 s36, s36, 0x2c0
	s_sub_i32 s36, s0, s36
	s_sub_i32 s35, s35, s34
	s_mul_hi_u32 s37, s36, 0x2e8ba2f
	s_mul_i32 s38, s37, 0x58
	s_sub_i32 s38, s36, s38
	s_lshr_b32 s39, s36, 5
	s_and_b32 s40, s36, 31
	s_cmp_eq_u32 s34, 1
	s_cselect_b32 s37, s37, s39
	s_cselect_b32 s38, s38, s40
	s_cselect_b32 s56, s52, s50
	s_cselect_b32 s57, s53, s51
	s_mov_b32 s59, 0x40000
	s_cselect_b32 s59, 0xb0000, s59
	s_mov_b32 s90, 0x100000
	s_cselect_b32 s90, 0x160000, s90
	s_mov_b32 s41, 0x140000
	s_cselect_b32 s41, 0x210000, s41
	s_mov_b32 s39, 0x200000
	s_cselect_b32 s39, 0x2c0000, s39
	s_cselect_b64 s[28:29], -1, 0
	s_mul_i32 s39, s37, s39
	s_lshl_b32 s40, s38, 7
	s_add_u32 s39, s39, s40
	s_lshl_b32 s40, s35, 19
	s_add_u32 s39, s39, s40
	s_add_u32 s56, s56, s39
	s_addc_u32 s57, s57, 0
	v_cndmask_b32_e64 v107, v104, v105, s[28:29]
	v_add_u32_e32 v108, s59, v107
	v_add_u32_e32 v109, s90, v107
	v_add_u32_e32 v110, s41, v107
	ds_read_b32 v80, v103 offset:33792
	ds_read_b32 v81, v103 offset:33796
	ds_read_b32 v82, v103 offset:33800
	ds_read_b32 v83, v103 offset:33804
	ds_read_b32 v84, v103 offset:42240
	ds_read_b32 v85, v103 offset:42244
	ds_read_b32 v86, v103 offset:42248
	ds_read_b32 v87, v103 offset:42252
	ds_read_b32 v88, v103 offset:50688
	ds_read_b32 v89, v103 offset:50692
	ds_read_b32 v90, v103 offset:50696
	ds_read_b32 v91, v103 offset:50700
	ds_read_b32 v92, v103 offset:59136
	ds_read_b32 v93, v103 offset:59140
	ds_read_b32 v94, v103 offset:59144
	ds_read_b32 v95, v103 offset:59148
	s_waitcnt lgkmcnt(0)
	global_store_dwordx4 v107, v[80:83], s[56:57]
	global_store_dwordx4 v108, v[84:87], s[56:57]
	global_store_dwordx4 v109, v[88:91], s[56:57]
	global_store_dwordx4 v110, v[92:95], s[56:57]
	s_add_i32 s0, s0, s2
	s_cmp_lt_u32 s0, 2112
	s_cbranch_scc1 .Lfcf_loop
